# v30: v28 + barrier waiters/releasers poll the top-level arrival counter (target (gen+1)*nx) instead of the generation word
# baseline (speedup 1.0000x reference)
.LBB0_96:
	s_or_b64 exec, exec, s[10:11]
	s_cmp_eq_u32 s0, 0
	s_cselect_b64 vcc, -1, 0
	s_cmp_eq_u32 s0, 1
	v_cndmask_b32_e32 v18, 1, v15, vcc
	s_cselect_b64 vcc, -1, 0
	s_cmp_eq_u32 s0, 2
	v_cndmask_b32_e32 v18, v18, v0, vcc
	s_cselect_b64 vcc, -1, 0
	s_cmp_eq_u32 s0, 3
	v_cndmask_b32_e32 v18, v18, v1, vcc
	s_cselect_b64 vcc, -1, 0
	s_cmp_eq_u32 s0, 4
	v_cndmask_b32_e32 v18, v18, v2, vcc
	s_cselect_b64 vcc, -1, 0
	s_cmp_eq_u32 s0, 5
	v_cndmask_b32_e32 v18, v18, v3, vcc
	s_cselect_b64 vcc, -1, 0
	s_cmp_eq_u32 s0, 6
	v_cndmask_b32_e32 v18, v18, v4, vcc
	s_cselect_b64 vcc, -1, 0
	s_cmp_eq_u32 s0, 7
	v_cndmask_b32_e32 v18, v18, v5, vcc
	s_cselect_b64 vcc, -1, 0
	s_cmp_eq_u32 s0, 8
	v_cndmask_b32_e32 v18, v18, v6, vcc
	s_cselect_b64 vcc, -1, 0
	s_cmp_eq_u32 s0, 9
	v_cndmask_b32_e32 v18, v18, v7, vcc
	s_cselect_b64 vcc, -1, 0
	s_cmp_eq_u32 s0, 10
	v_cndmask_b32_e32 v18, v18, v8, vcc
	s_cselect_b64 vcc, -1, 0
	s_cmp_eq_u32 s0, 11
	v_cndmask_b32_e32 v18, v18, v9, vcc
	s_cselect_b64 vcc, -1, 0
	s_cmp_eq_u32 s0, 12
	v_cndmask_b32_e32 v18, v18, v10, vcc
	s_cselect_b64 vcc, -1, 0
	s_cmp_eq_u32 s0, 13
	v_cndmask_b32_e32 v18, v18, v11, vcc
	s_cselect_b64 vcc, -1, 0
	s_cmp_eq_u32 s0, 14
	v_cndmask_b32_e32 v18, v18, v12, vcc
	s_cselect_b64 vcc, -1, 0
	s_cmp_eq_u32 s0, 15
	v_cndmask_b32_e32 v18, v18, v13, vcc
	s_cselect_b64 vcc, -1, 0
	v_cndmask_b32_e32 v18, v18, v14, vcc
	v_cvt_f32_u32_e32 v19, v18
	s_waitcnt vmcnt(0)
	v_readfirstlane_b32 s0, v17
	v_rcp_iflag_f32_e32 v19, v19
	s_nop 0
	v_add_u32_e32 v17, s0, v16
	v_sub_u32_e32 v16, 0, v18
	v_mul_f32_e32 v19, 0x4f7ffffe, v19
	v_cvt_u32_f32_e32 v19, v19
	v_mul_lo_u32 v16, v16, v19
	v_mul_hi_u32 v16, v19, v16
	v_add_u32_e32 v16, v19, v16
	v_mul_hi_u32 v16, v17, v16
	v_mul_lo_u32 v19, v16, v18
	v_sub_u32_e32 v19, v17, v19
	v_add_u32_e32 v20, 1, v16
	v_cmp_ge_u32_e32 vcc, v19, v18
	v_add_u32_e32 v17, 1, v17
	s_nop 0
	v_cndmask_b32_e32 v16, v16, v20, vcc
	v_sub_u32_e32 v20, v19, v18
	v_cndmask_b32_e32 v19, v19, v20, vcc
	v_add_u32_e32 v20, 1, v16
	v_cmp_ge_u32_e32 vcc, v19, v18
	s_nop 1
	v_cndmask_b32_e32 v16, v16, v20, vcc
	v_mul_lo_u32 v19, v18, v16
	v_add_u32_e32 v18, v19, v18
	v_cmp_ne_u32_e32 vcc, v17, v18
	s_and_saveexec_b64 s[0:1], vcc
	s_xor_b64 s[8:9], exec, s[0:1]
	s_cbranch_execz .LBB0_101
	v_cmp_ne_u32_e32 vcc, 0, v15
	s_nop 1
	v_cndmask_b32_e64 v19, 0, 1, vcc
	v_cmp_ne_u32_e32 vcc, 0, v0
	s_nop 1
	v_addc_co_u32_e32 v19, vcc, 0, v19, vcc
	v_cmp_ne_u32_e32 vcc, 0, v1
	s_nop 1
	v_addc_co_u32_e32 v19, vcc, 0, v19, vcc
	v_cmp_ne_u32_e32 vcc, 0, v2
	s_nop 1
	v_addc_co_u32_e32 v19, vcc, 0, v19, vcc
	v_cmp_ne_u32_e32 vcc, 0, v3
	s_nop 1
	v_addc_co_u32_e32 v19, vcc, 0, v19, vcc
	v_cmp_ne_u32_e32 vcc, 0, v4
	s_nop 1
	v_addc_co_u32_e32 v19, vcc, 0, v19, vcc
	v_cmp_ne_u32_e32 vcc, 0, v5
	s_nop 1
	v_addc_co_u32_e32 v19, vcc, 0, v19, vcc
	v_cmp_ne_u32_e32 vcc, 0, v6
	s_nop 1
	v_addc_co_u32_e32 v19, vcc, 0, v19, vcc
	v_cmp_ne_u32_e32 vcc, 0, v7
	s_nop 1
	v_addc_co_u32_e32 v19, vcc, 0, v19, vcc
	v_cmp_ne_u32_e32 vcc, 0, v8
	s_nop 1
	v_addc_co_u32_e32 v19, vcc, 0, v19, vcc
	v_cmp_ne_u32_e32 vcc, 0, v9
	s_nop 1
	v_addc_co_u32_e32 v19, vcc, 0, v19, vcc
	v_cmp_ne_u32_e32 vcc, 0, v10
	s_nop 1
	v_addc_co_u32_e32 v19, vcc, 0, v19, vcc
	v_cmp_ne_u32_e32 vcc, 0, v11
	s_nop 1
	v_addc_co_u32_e32 v19, vcc, 0, v19, vcc
	v_cmp_ne_u32_e32 vcc, 0, v12
	s_nop 1
	v_addc_co_u32_e32 v19, vcc, 0, v19, vcc
	v_cmp_ne_u32_e32 vcc, 0, v13
	s_nop 1
	v_addc_co_u32_e32 v19, vcc, 0, v19, vcc
	v_cmp_ne_u32_e32 vcc, 0, v14
	s_nop 1
	v_addc_co_u32_e32 v19, vcc, 0, v19, vcc
	v_add_u32_e32 v20, 1, v16
	v_mul_lo_u32 v20, v20, v19
	s_add_u32 s10, s70, 0x3400
	s_addc_u32 s11, s71, 0
	v_mov_b32_e32 v17, 0
	global_load_dword v17, v17, s[10:11] sc1
	s_waitcnt vmcnt(0)
	v_cmp_lt_u32_e32 vcc, v17, v20
	s_and_saveexec_b64 s[28:29], vcc
	s_cbranch_execz .LBB0_100
	s_mov_b64 s[30:31], 0
	v_mov_b32_e32 v17, 0
.LBB0_99:
	s_sleep 1
	global_load_dword v18, v17, s[10:11] sc1
	s_waitcnt vmcnt(0)
	v_cmp_ge_u32_e32 vcc, v18, v20
	s_or_b64 s[30:31], vcc, s[30:31]
	s_andn2_b64 exec, exec, s[30:31]
	s_cbranch_execnz .LBB0_99

.LBB0_104:
	s_or_b64 exec, exec, s[10:11]
	v_cmp_ne_u32_e32 vcc, 0, v15
	s_waitcnt vmcnt(0)
	v_readfirstlane_b32 s0, v17
	s_add_u32 s8, s70, 0x3500
	v_cndmask_b32_e64 v15, 0, 1, vcc
	v_cmp_ne_u32_e32 vcc, 0, v0
	s_addc_u32 s9, s71, 0
	s_nop 0
	v_addc_co_u32_e32 v0, vcc, 0, v15, vcc
	v_cmp_ne_u32_e32 vcc, 0, v1
	s_nop 1
	v_cndmask_b32_e64 v1, 0, 1, vcc
	v_cmp_ne_u32_e32 vcc, 0, v2
	v_add_u32_e32 v2, s0, v16
	s_nop 0
	v_addc_co_u32_e32 v0, vcc, v0, v1, vcc
	v_cmp_ne_u32_e32 vcc, 0, v3
	s_nop 1
	v_cndmask_b32_e64 v1, 0, 1, vcc
	v_cmp_ne_u32_e32 vcc, 0, v4
	s_nop 1
	v_addc_co_u32_e32 v0, vcc, v0, v1, vcc
	v_cmp_ne_u32_e32 vcc, 0, v5
	s_nop 1
	v_cndmask_b32_e64 v1, 0, 1, vcc
	v_cmp_ne_u32_e32 vcc, 0, v6
	s_nop 1
	v_addc_co_u32_e32 v0, vcc, v0, v1, vcc
	v_cmp_ne_u32_e32 vcc, 0, v7
	s_nop 1
	v_cndmask_b32_e64 v1, 0, 1, vcc
	v_cmp_ne_u32_e32 vcc, 0, v8
	s_nop 1
	v_addc_co_u32_e32 v0, vcc, v0, v1, vcc
	v_cmp_ne_u32_e32 vcc, 0, v9
	s_nop 1
	v_cndmask_b32_e64 v1, 0, 1, vcc
	v_cmp_ne_u32_e32 vcc, 0, v10
	s_nop 1
	v_addc_co_u32_e32 v0, vcc, v0, v1, vcc
	v_cmp_ne_u32_e32 vcc, 0, v11
	s_nop 1
	v_cndmask_b32_e64 v1, 0, 1, vcc
	v_cmp_ne_u32_e32 vcc, 0, v12
	s_nop 1
	v_addc_co_u32_e32 v0, vcc, v0, v1, vcc
	v_cmp_ne_u32_e32 vcc, 0, v13
	s_nop 1
	v_cndmask_b32_e64 v1, 0, 1, vcc
	v_cmp_ne_u32_e32 vcc, 0, v14
	s_nop 1
	v_addc_co_u32_e32 v1, vcc, v0, v1, vcc
	v_cvt_f32_u32_e32 v0, v1
	v_sub_u32_e32 v3, 0, v1
	v_rcp_iflag_f32_e32 v0, v0
	s_nop 0
	v_mul_f32_e32 v0, 0x4f7ffffe, v0
	v_cvt_u32_f32_e32 v0, v0
	v_mul_lo_u32 v3, v3, v0
	v_mul_hi_u32 v3, v0, v3
	v_add_u32_e32 v0, v0, v3
	v_mul_hi_u32 v0, v2, v0
	v_mul_lo_u32 v3, v0, v1
	v_sub_u32_e32 v3, v2, v3
	v_add_u32_e32 v4, 1, v0
	v_cmp_ge_u32_e32 vcc, v3, v1
	v_add_u32_e32 v2, 1, v2
	s_nop 0
	v_cndmask_b32_e32 v0, v0, v4, vcc
	v_sub_u32_e32 v4, v3, v1
	v_cndmask_b32_e32 v3, v3, v4, vcc
	v_add_u32_e32 v4, 1, v0
	v_cmp_ge_u32_e32 vcc, v3, v1
	s_nop 1
	v_cndmask_b32_e32 v0, v0, v4, vcc
	v_mul_lo_u32 v3, v1, v0
	v_add_u32_e32 v1, v3, v1
	v_cmp_ne_u32_e32 vcc, v2, v1
	s_and_saveexec_b64 s[0:1], vcc
	s_xor_b64 s[10:11], exec, s[0:1]
	s_cbranch_execz .LBB0_109
	v_mov_b32_e32 v4, v1
	v_mov_b32_e32 v1, 0
	global_load_dword v2, v1, s[8:9] offset:-256 sc1
	s_waitcnt vmcnt(0)
	v_cmp_lt_u32_e32 vcc, v2, v4
	s_and_saveexec_b64 s[28:29], vcc
	s_cbranch_execz .LBB0_108
	s_mov_b64 s[30:31], 0
.LBB0_107:
	s_sleep 1
	global_load_dword v2, v1, s[8:9] offset:-256 sc1
	s_waitcnt vmcnt(0)
	v_cmp_ge_u32_e32 vcc, v2, v4
	s_or_b64 s[30:31], vcc, s[30:31]
	s_andn2_b64 exec, exec, s[30:31]
	s_cbranch_execnz .LBB0_107

.LBB0_285:
	s_or_b64 exec, exec, s[10:11]
	s_waitcnt vmcnt(0)
	s_cmp_eq_u32 s0, 0
	s_cselect_b64 vcc, -1, 0
	s_cmp_eq_u32 s0, 1
	v_cndmask_b32_e32 v18, 1, v15, vcc
	s_cselect_b64 vcc, -1, 0
	s_cmp_eq_u32 s0, 2
	v_cndmask_b32_e32 v18, v18, v0, vcc
	s_cselect_b64 vcc, -1, 0
	s_cmp_eq_u32 s0, 3
	v_cndmask_b32_e32 v18, v18, v1, vcc
	s_cselect_b64 vcc, -1, 0
	s_cmp_eq_u32 s0, 4
	v_cndmask_b32_e32 v18, v18, v2, vcc
	s_cselect_b64 vcc, -1, 0
	s_cmp_eq_u32 s0, 5
	v_cndmask_b32_e32 v18, v18, v3, vcc
	s_cselect_b64 vcc, -1, 0
	s_cmp_eq_u32 s0, 6
	v_cndmask_b32_e32 v18, v18, v4, vcc
	s_cselect_b64 vcc, -1, 0
	s_cmp_eq_u32 s0, 7
	v_cndmask_b32_e32 v18, v18, v5, vcc
	s_cselect_b64 vcc, -1, 0
	s_cmp_eq_u32 s0, 8
	v_cndmask_b32_e32 v18, v18, v6, vcc
	s_cselect_b64 vcc, -1, 0
	s_cmp_eq_u32 s0, 9
	v_cndmask_b32_e32 v18, v18, v7, vcc
	s_cselect_b64 vcc, -1, 0
	s_cmp_eq_u32 s0, 10
	v_cndmask_b32_e32 v18, v18, v8, vcc
	s_cselect_b64 vcc, -1, 0
	s_cmp_eq_u32 s0, 11
	v_cndmask_b32_e32 v18, v18, v9, vcc
	s_cselect_b64 vcc, -1, 0
	s_cmp_eq_u32 s0, 12
	v_cndmask_b32_e32 v18, v18, v10, vcc
	s_cselect_b64 vcc, -1, 0
	s_cmp_eq_u32 s0, 13
	v_cndmask_b32_e32 v18, v18, v11, vcc
	s_cselect_b64 vcc, -1, 0
	s_cmp_eq_u32 s0, 14
	v_cndmask_b32_e32 v18, v18, v12, vcc
	s_cselect_b64 vcc, -1, 0
	s_cmp_eq_u32 s0, 15
	v_cndmask_b32_e32 v18, v18, v13, vcc
	s_cselect_b64 vcc, -1, 0
	v_cndmask_b32_e32 v18, v18, v14, vcc
	v_cvt_f32_u32_e32 v19, v18
	s_waitcnt vmcnt(0)
	v_readfirstlane_b32 s0, v17
	v_rcp_iflag_f32_e32 v19, v19
	s_nop 0
	v_add_u32_e32 v17, s0, v16
	v_sub_u32_e32 v16, 0, v18
	v_mul_f32_e32 v19, 0x4f7ffffe, v19
	v_cvt_u32_f32_e32 v19, v19
	v_mul_lo_u32 v16, v16, v19
	v_mul_hi_u32 v16, v19, v16
	v_add_u32_e32 v16, v19, v16
	v_mul_hi_u32 v16, v17, v16
	v_mul_lo_u32 v19, v16, v18
	v_sub_u32_e32 v19, v17, v19
	v_add_u32_e32 v20, 1, v16
	v_cmp_ge_u32_e32 vcc, v19, v18
	v_add_u32_e32 v17, 1, v17
	s_nop 0
	v_cndmask_b32_e32 v16, v16, v20, vcc
	v_sub_u32_e32 v20, v19, v18
	v_cndmask_b32_e32 v19, v19, v20, vcc
	v_add_u32_e32 v20, 1, v16
	v_cmp_ge_u32_e32 vcc, v19, v18
	s_nop 1
	v_cndmask_b32_e32 v16, v16, v20, vcc
	v_mul_lo_u32 v19, v18, v16
	v_add_u32_e32 v18, v19, v18
	v_cmp_ne_u32_e32 vcc, v17, v18
	s_and_saveexec_b64 s[0:1], vcc
	s_xor_b64 s[8:9], exec, s[0:1]
	s_cbranch_execz .LBB0_290
	v_cmp_ne_u32_e32 vcc, 0, v15
	s_nop 1
	v_cndmask_b32_e64 v19, 0, 1, vcc
	v_cmp_ne_u32_e32 vcc, 0, v0
	s_nop 1
	v_addc_co_u32_e32 v19, vcc, 0, v19, vcc
	v_cmp_ne_u32_e32 vcc, 0, v1
	s_nop 1
	v_addc_co_u32_e32 v19, vcc, 0, v19, vcc
	v_cmp_ne_u32_e32 vcc, 0, v2
	s_nop 1
	v_addc_co_u32_e32 v19, vcc, 0, v19, vcc
	v_cmp_ne_u32_e32 vcc, 0, v3
	s_nop 1
	v_addc_co_u32_e32 v19, vcc, 0, v19, vcc
	v_cmp_ne_u32_e32 vcc, 0, v4
	s_nop 1
	v_addc_co_u32_e32 v19, vcc, 0, v19, vcc
	v_cmp_ne_u32_e32 vcc, 0, v5
	s_nop 1
	v_addc_co_u32_e32 v19, vcc, 0, v19, vcc
	v_cmp_ne_u32_e32 vcc, 0, v6
	s_nop 1
	v_addc_co_u32_e32 v19, vcc, 0, v19, vcc
	v_cmp_ne_u32_e32 vcc, 0, v7
	s_nop 1
	v_addc_co_u32_e32 v19, vcc, 0, v19, vcc
	v_cmp_ne_u32_e32 vcc, 0, v8
	s_nop 1
	v_addc_co_u32_e32 v19, vcc, 0, v19, vcc
	v_cmp_ne_u32_e32 vcc, 0, v9
	s_nop 1
	v_addc_co_u32_e32 v19, vcc, 0, v19, vcc
	v_cmp_ne_u32_e32 vcc, 0, v10
	s_nop 1
	v_addc_co_u32_e32 v19, vcc, 0, v19, vcc
	v_cmp_ne_u32_e32 vcc, 0, v11
	s_nop 1
	v_addc_co_u32_e32 v19, vcc, 0, v19, vcc
	v_cmp_ne_u32_e32 vcc, 0, v12
	s_nop 1
	v_addc_co_u32_e32 v19, vcc, 0, v19, vcc
	v_cmp_ne_u32_e32 vcc, 0, v13
	s_nop 1
	v_addc_co_u32_e32 v19, vcc, 0, v19, vcc
	v_cmp_ne_u32_e32 vcc, 0, v14
	s_nop 1
	v_addc_co_u32_e32 v19, vcc, 0, v19, vcc
	v_add_u32_e32 v20, 1, v16
	v_mul_lo_u32 v20, v20, v19
	s_add_u32 s10, s70, 0x3400
	s_addc_u32 s11, s71, 0
	v_mov_b32_e32 v17, 0
	global_load_dword v17, v17, s[10:11] sc1
	s_waitcnt vmcnt(0)
	v_cmp_lt_u32_e32 vcc, v17, v20
	s_and_saveexec_b64 s[28:29], vcc
	s_cbranch_execz .LBB0_289
	s_mov_b64 s[30:31], 0
	v_mov_b32_e32 v17, 0

.LBB0_569:
	s_or_b64 exec, exec, s[10:11]
	s_waitcnt vmcnt(0)
	s_cmp_eq_u32 s0, 0
	s_cselect_b64 vcc, -1, 0
	s_cmp_eq_u32 s0, 1
	v_cndmask_b32_e32 v18, 1, v15, vcc
	s_cselect_b64 vcc, -1, 0
	s_cmp_eq_u32 s0, 2
	v_cndmask_b32_e32 v18, v18, v0, vcc
	s_cselect_b64 vcc, -1, 0
	s_cmp_eq_u32 s0, 3
	v_cndmask_b32_e32 v18, v18, v1, vcc
	s_cselect_b64 vcc, -1, 0
	s_cmp_eq_u32 s0, 4
	v_cndmask_b32_e32 v18, v18, v2, vcc
	s_cselect_b64 vcc, -1, 0
	s_cmp_eq_u32 s0, 5
	v_cndmask_b32_e32 v18, v18, v3, vcc
	s_cselect_b64 vcc, -1, 0
	s_cmp_eq_u32 s0, 6
	v_cndmask_b32_e32 v18, v18, v4, vcc
	s_cselect_b64 vcc, -1, 0
	s_cmp_eq_u32 s0, 7
	v_cndmask_b32_e32 v18, v18, v5, vcc
	s_cselect_b64 vcc, -1, 0
	s_cmp_eq_u32 s0, 8
	v_cndmask_b32_e32 v18, v18, v6, vcc
	s_cselect_b64 vcc, -1, 0
	s_cmp_eq_u32 s0, 9
	v_cndmask_b32_e32 v18, v18, v7, vcc
	s_cselect_b64 vcc, -1, 0
	s_cmp_eq_u32 s0, 10
	v_cndmask_b32_e32 v18, v18, v8, vcc
	s_cselect_b64 vcc, -1, 0
	s_cmp_eq_u32 s0, 11
	v_cndmask_b32_e32 v18, v18, v9, vcc
	s_cselect_b64 vcc, -1, 0
	s_cmp_eq_u32 s0, 12
	v_cndmask_b32_e32 v18, v18, v10, vcc
	s_cselect_b64 vcc, -1, 0
	s_cmp_eq_u32 s0, 13
	v_cndmask_b32_e32 v18, v18, v11, vcc
	s_cselect_b64 vcc, -1, 0
	s_cmp_eq_u32 s0, 14
	v_cndmask_b32_e32 v18, v18, v12, vcc
	s_cselect_b64 vcc, -1, 0
	s_cmp_eq_u32 s0, 15
	v_cndmask_b32_e32 v18, v18, v13, vcc
	s_cselect_b64 vcc, -1, 0
	v_cndmask_b32_e32 v18, v18, v14, vcc
	v_cvt_f32_u32_e32 v19, v18
	s_waitcnt vmcnt(0)
	v_readfirstlane_b32 s0, v17
	v_rcp_iflag_f32_e32 v19, v19
	s_nop 0
	v_add_u32_e32 v17, s0, v16
	v_sub_u32_e32 v16, 0, v18
	v_mul_f32_e32 v19, 0x4f7ffffe, v19
	v_cvt_u32_f32_e32 v19, v19
	v_mul_lo_u32 v16, v16, v19
	v_mul_hi_u32 v16, v19, v16
	v_add_u32_e32 v16, v19, v16
	v_mul_hi_u32 v16, v17, v16
	v_mul_lo_u32 v19, v16, v18
	v_sub_u32_e32 v19, v17, v19
	v_add_u32_e32 v20, 1, v16
	v_cmp_ge_u32_e32 vcc, v19, v18
	v_add_u32_e32 v17, 1, v17
	s_nop 0
	v_cndmask_b32_e32 v16, v16, v20, vcc
	v_sub_u32_e32 v20, v19, v18
	v_cndmask_b32_e32 v19, v19, v20, vcc
	v_add_u32_e32 v20, 1, v16
	v_cmp_ge_u32_e32 vcc, v19, v18
	s_nop 1
	v_cndmask_b32_e32 v16, v16, v20, vcc
	v_mul_lo_u32 v19, v18, v16
	v_add_u32_e32 v18, v19, v18
	v_cmp_ne_u32_e32 vcc, v17, v18
	s_and_saveexec_b64 s[0:1], vcc
	s_xor_b64 s[8:9], exec, s[0:1]
	s_cbranch_execz .LBB0_574
	v_cmp_ne_u32_e32 vcc, 0, v15
	s_nop 1
	v_cndmask_b32_e64 v19, 0, 1, vcc
	v_cmp_ne_u32_e32 vcc, 0, v0
	s_nop 1
	v_addc_co_u32_e32 v19, vcc, 0, v19, vcc
	v_cmp_ne_u32_e32 vcc, 0, v1
	s_nop 1
	v_addc_co_u32_e32 v19, vcc, 0, v19, vcc
	v_cmp_ne_u32_e32 vcc, 0, v2
	s_nop 1
	v_addc_co_u32_e32 v19, vcc, 0, v19, vcc
	v_cmp_ne_u32_e32 vcc, 0, v3
	s_nop 1
	v_addc_co_u32_e32 v19, vcc, 0, v19, vcc
	v_cmp_ne_u32_e32 vcc, 0, v4
	s_nop 1
	v_addc_co_u32_e32 v19, vcc, 0, v19, vcc
	v_cmp_ne_u32_e32 vcc, 0, v5
	s_nop 1
	v_addc_co_u32_e32 v19, vcc, 0, v19, vcc
	v_cmp_ne_u32_e32 vcc, 0, v6
	s_nop 1
	v_addc_co_u32_e32 v19, vcc, 0, v19, vcc
	v_cmp_ne_u32_e32 vcc, 0, v7
	s_nop 1
	v_addc_co_u32_e32 v19, vcc, 0, v19, vcc
	v_cmp_ne_u32_e32 vcc, 0, v8
	s_nop 1
	v_addc_co_u32_e32 v19, vcc, 0, v19, vcc
	v_cmp_ne_u32_e32 vcc, 0, v9
	s_nop 1
	v_addc_co_u32_e32 v19, vcc, 0, v19, vcc
	v_cmp_ne_u32_e32 vcc, 0, v10
	s_nop 1
	v_addc_co_u32_e32 v19, vcc, 0, v19, vcc
	v_cmp_ne_u32_e32 vcc, 0, v11
	s_nop 1
	v_addc_co_u32_e32 v19, vcc, 0, v19, vcc
	v_cmp_ne_u32_e32 vcc, 0, v12
	s_nop 1
	v_addc_co_u32_e32 v19, vcc, 0, v19, vcc
	v_cmp_ne_u32_e32 vcc, 0, v13
	s_nop 1
	v_addc_co_u32_e32 v19, vcc, 0, v19, vcc
	v_cmp_ne_u32_e32 vcc, 0, v14
	s_nop 1
	v_addc_co_u32_e32 v19, vcc, 0, v19, vcc
	v_add_u32_e32 v20, 1, v16
	v_mul_lo_u32 v20, v20, v19
	s_add_u32 s10, s70, 0x3400
	s_addc_u32 s11, s71, 0
	v_mov_b32_e32 v17, 0
	global_load_dword v17, v17, s[10:11] sc1
	s_waitcnt vmcnt(0)
	v_cmp_lt_u32_e32 vcc, v17, v20
	s_and_saveexec_b64 s[12:13], vcc
	s_cbranch_execz .LBB0_573
	s_mov_b64 s[14:15], 0
	v_mov_b32_e32 v17, 0
.LBB0_572:
	s_sleep 1
	global_load_dword v18, v17, s[10:11] sc1
	s_waitcnt vmcnt(0)
	v_cmp_ge_u32_e32 vcc, v18, v20
	s_or_b64 s[14:15], vcc, s[14:15]
	s_andn2_b64 exec, exec, s[14:15]
	s_cbranch_execnz .LBB0_572

.LBB0_577:
	s_or_b64 exec, exec, s[10:11]
	v_cmp_ne_u32_e32 vcc, 0, v15
	s_waitcnt vmcnt(0)
	v_readfirstlane_b32 s0, v17
	s_add_u32 s8, s70, 0x3500
	v_cndmask_b32_e64 v15, 0, 1, vcc
	v_cmp_ne_u32_e32 vcc, 0, v0
	s_addc_u32 s9, s71, 0
	s_nop 0
	v_addc_co_u32_e32 v0, vcc, 0, v15, vcc
	v_cmp_ne_u32_e32 vcc, 0, v1
	s_nop 1
	v_cndmask_b32_e64 v1, 0, 1, vcc
	v_cmp_ne_u32_e32 vcc, 0, v2
	v_add_u32_e32 v2, s0, v16
	s_nop 0
	v_addc_co_u32_e32 v0, vcc, v0, v1, vcc
	v_cmp_ne_u32_e32 vcc, 0, v3
	s_nop 1
	v_cndmask_b32_e64 v1, 0, 1, vcc
	v_cmp_ne_u32_e32 vcc, 0, v4
	s_nop 1
	v_addc_co_u32_e32 v0, vcc, v0, v1, vcc
	v_cmp_ne_u32_e32 vcc, 0, v5
	s_nop 1
	v_cndmask_b32_e64 v1, 0, 1, vcc
	v_cmp_ne_u32_e32 vcc, 0, v6
	s_nop 1
	v_addc_co_u32_e32 v0, vcc, v0, v1, vcc
	v_cmp_ne_u32_e32 vcc, 0, v7
	s_nop 1
	v_cndmask_b32_e64 v1, 0, 1, vcc
	v_cmp_ne_u32_e32 vcc, 0, v8
	s_nop 1
	v_addc_co_u32_e32 v0, vcc, v0, v1, vcc
	v_cmp_ne_u32_e32 vcc, 0, v9
	s_nop 1
	v_cndmask_b32_e64 v1, 0, 1, vcc
	v_cmp_ne_u32_e32 vcc, 0, v10
	s_nop 1
	v_addc_co_u32_e32 v0, vcc, v0, v1, vcc
	v_cmp_ne_u32_e32 vcc, 0, v11
	s_nop 1
	v_cndmask_b32_e64 v1, 0, 1, vcc
	v_cmp_ne_u32_e32 vcc, 0, v12
	s_nop 1
	v_addc_co_u32_e32 v0, vcc, v0, v1, vcc
	v_cmp_ne_u32_e32 vcc, 0, v13
	s_nop 1
	v_cndmask_b32_e64 v1, 0, 1, vcc
	v_cmp_ne_u32_e32 vcc, 0, v14
	s_nop 1
	v_addc_co_u32_e32 v1, vcc, v0, v1, vcc
	v_cvt_f32_u32_e32 v0, v1
	v_sub_u32_e32 v3, 0, v1
	v_rcp_iflag_f32_e32 v0, v0
	s_nop 0
	v_mul_f32_e32 v0, 0x4f7ffffe, v0
	v_cvt_u32_f32_e32 v0, v0
	v_mul_lo_u32 v3, v3, v0
	v_mul_hi_u32 v3, v0, v3
	v_add_u32_e32 v0, v0, v3
	v_mul_hi_u32 v0, v2, v0
	v_mul_lo_u32 v3, v0, v1
	v_sub_u32_e32 v3, v2, v3
	v_add_u32_e32 v4, 1, v0
	v_cmp_ge_u32_e32 vcc, v3, v1
	v_add_u32_e32 v2, 1, v2
	s_nop 0
	v_cndmask_b32_e32 v0, v0, v4, vcc
	v_sub_u32_e32 v4, v3, v1
	v_cndmask_b32_e32 v3, v3, v4, vcc
	v_add_u32_e32 v4, 1, v0
	v_cmp_ge_u32_e32 vcc, v3, v1
	s_nop 1
	v_cndmask_b32_e32 v0, v0, v4, vcc
	v_mul_lo_u32 v3, v1, v0
	v_add_u32_e32 v1, v3, v1
	v_cmp_ne_u32_e32 vcc, v2, v1
	s_and_saveexec_b64 s[0:1], vcc
	s_xor_b64 s[10:11], exec, s[0:1]
	s_cbranch_execz .LBB0_582
	v_mov_b32_e32 v4, v1
	v_mov_b32_e32 v1, 0
	global_load_dword v2, v1, s[8:9] offset:-256 sc1
	s_waitcnt vmcnt(0)
	v_cmp_lt_u32_e32 vcc, v2, v4
	s_and_saveexec_b64 s[12:13], vcc
	s_cbranch_execz .LBB0_581
	s_mov_b64 s[14:15], 0
.LBB0_580:
	s_sleep 1
	global_load_dword v2, v1, s[8:9] offset:-256 sc1
	s_waitcnt vmcnt(0)
	v_cmp_ge_u32_e32 vcc, v2, v4
	s_or_b64 s[14:15], vcc, s[14:15]
	s_andn2_b64 exec, exec, s[14:15]
	s_cbranch_execnz .LBB0_580

.LBB0_878:
	s_or_b64 exec, exec, s[10:11]
	s_cmp_eq_u32 s0, 0
	s_cselect_b64 vcc, -1, 0
	s_cmp_eq_u32 s0, 1
	v_cndmask_b32_e32 v18, 1, v15, vcc
	s_cselect_b64 vcc, -1, 0
	s_cmp_eq_u32 s0, 2
	v_cndmask_b32_e32 v18, v18, v0, vcc
	s_cselect_b64 vcc, -1, 0
	s_cmp_eq_u32 s0, 3
	v_cndmask_b32_e32 v18, v18, v1, vcc
	s_cselect_b64 vcc, -1, 0
	s_cmp_eq_u32 s0, 4
	v_cndmask_b32_e32 v18, v18, v2, vcc
	s_cselect_b64 vcc, -1, 0
	s_cmp_eq_u32 s0, 5
	v_cndmask_b32_e32 v18, v18, v3, vcc
	s_cselect_b64 vcc, -1, 0
	s_cmp_eq_u32 s0, 6
	v_cndmask_b32_e32 v18, v18, v4, vcc
	s_cselect_b64 vcc, -1, 0
	s_cmp_eq_u32 s0, 7
	v_cndmask_b32_e32 v18, v18, v5, vcc
	s_cselect_b64 vcc, -1, 0
	s_cmp_eq_u32 s0, 8
	v_cndmask_b32_e32 v18, v18, v6, vcc
	s_cselect_b64 vcc, -1, 0
	s_cmp_eq_u32 s0, 9
	v_cndmask_b32_e32 v18, v18, v7, vcc
	s_cselect_b64 vcc, -1, 0
	s_cmp_eq_u32 s0, 10
	v_cndmask_b32_e32 v18, v18, v8, vcc
	s_cselect_b64 vcc, -1, 0
	s_cmp_eq_u32 s0, 11
	v_cndmask_b32_e32 v18, v18, v9, vcc
	s_cselect_b64 vcc, -1, 0
	s_cmp_eq_u32 s0, 12
	v_cndmask_b32_e32 v18, v18, v10, vcc
	s_cselect_b64 vcc, -1, 0
	s_cmp_eq_u32 s0, 13
	v_cndmask_b32_e32 v18, v18, v11, vcc
	s_cselect_b64 vcc, -1, 0
	s_cmp_eq_u32 s0, 14
	v_cndmask_b32_e32 v18, v18, v12, vcc
	s_cselect_b64 vcc, -1, 0
	s_cmp_eq_u32 s0, 15
	v_cndmask_b32_e32 v18, v18, v13, vcc
	s_cselect_b64 vcc, -1, 0
	v_cndmask_b32_e32 v18, v18, v14, vcc
	v_cvt_f32_u32_e32 v19, v18
	s_waitcnt vmcnt(0)
	v_readfirstlane_b32 s0, v17
	v_rcp_iflag_f32_e32 v19, v19
	s_nop 0
	v_add_u32_e32 v17, s0, v16
	v_sub_u32_e32 v16, 0, v18
	v_mul_f32_e32 v19, 0x4f7ffffe, v19
	v_cvt_u32_f32_e32 v19, v19
	v_mul_lo_u32 v16, v16, v19
	v_mul_hi_u32 v16, v19, v16
	v_add_u32_e32 v16, v19, v16
	v_mul_hi_u32 v16, v17, v16
	v_mul_lo_u32 v19, v16, v18
	v_sub_u32_e32 v19, v17, v19
	v_add_u32_e32 v20, 1, v16
	v_cmp_ge_u32_e32 vcc, v19, v18
	v_add_u32_e32 v17, 1, v17
	s_nop 0
	v_cndmask_b32_e32 v16, v16, v20, vcc
	v_sub_u32_e32 v20, v19, v18
	v_cndmask_b32_e32 v19, v19, v20, vcc
	v_add_u32_e32 v20, 1, v16
	v_cmp_ge_u32_e32 vcc, v19, v18
	s_nop 1
	v_cndmask_b32_e32 v16, v16, v20, vcc
	v_mul_lo_u32 v19, v18, v16
	v_add_u32_e32 v18, v19, v18
	v_cmp_ne_u32_e32 vcc, v17, v18
	s_and_saveexec_b64 s[0:1], vcc
	s_xor_b64 s[8:9], exec, s[0:1]
	s_cbranch_execz .LBB0_883
	v_cmp_ne_u32_e32 vcc, 0, v15
	s_nop 1
	v_cndmask_b32_e64 v19, 0, 1, vcc
	v_cmp_ne_u32_e32 vcc, 0, v0
	s_nop 1
	v_addc_co_u32_e32 v19, vcc, 0, v19, vcc
	v_cmp_ne_u32_e32 vcc, 0, v1
	s_nop 1
	v_addc_co_u32_e32 v19, vcc, 0, v19, vcc
	v_cmp_ne_u32_e32 vcc, 0, v2
	s_nop 1
	v_addc_co_u32_e32 v19, vcc, 0, v19, vcc
	v_cmp_ne_u32_e32 vcc, 0, v3
	s_nop 1
	v_addc_co_u32_e32 v19, vcc, 0, v19, vcc
	v_cmp_ne_u32_e32 vcc, 0, v4
	s_nop 1
	v_addc_co_u32_e32 v19, vcc, 0, v19, vcc
	v_cmp_ne_u32_e32 vcc, 0, v5
	s_nop 1
	v_addc_co_u32_e32 v19, vcc, 0, v19, vcc
	v_cmp_ne_u32_e32 vcc, 0, v6
	s_nop 1
	v_addc_co_u32_e32 v19, vcc, 0, v19, vcc
	v_cmp_ne_u32_e32 vcc, 0, v7
	s_nop 1
	v_addc_co_u32_e32 v19, vcc, 0, v19, vcc
	v_cmp_ne_u32_e32 vcc, 0, v8
	s_nop 1
	v_addc_co_u32_e32 v19, vcc, 0, v19, vcc
	v_cmp_ne_u32_e32 vcc, 0, v9
	s_nop 1
	v_addc_co_u32_e32 v19, vcc, 0, v19, vcc
	v_cmp_ne_u32_e32 vcc, 0, v10
	s_nop 1
	v_addc_co_u32_e32 v19, vcc, 0, v19, vcc
	v_cmp_ne_u32_e32 vcc, 0, v11
	s_nop 1
	v_addc_co_u32_e32 v19, vcc, 0, v19, vcc
	v_cmp_ne_u32_e32 vcc, 0, v12
	s_nop 1
	v_addc_co_u32_e32 v19, vcc, 0, v19, vcc
	v_cmp_ne_u32_e32 vcc, 0, v13
	s_nop 1
	v_addc_co_u32_e32 v19, vcc, 0, v19, vcc
	v_cmp_ne_u32_e32 vcc, 0, v14
	s_nop 1
	v_addc_co_u32_e32 v19, vcc, 0, v19, vcc
	v_add_u32_e32 v20, 1, v16
	v_mul_lo_u32 v20, v20, v19
	s_add_u32 s10, s70, 0x3400
	s_addc_u32 s11, s71, 0
	v_mov_b32_e32 v17, 0
	global_load_dword v17, v17, s[10:11] sc1
	s_waitcnt vmcnt(0)
	v_cmp_lt_u32_e32 vcc, v17, v20
	s_and_saveexec_b64 s[14:15], vcc
	s_cbranch_execz .LBB0_882
	s_mov_b64 s[20:21], 0
	v_mov_b32_e32 v17, 0
.LBB0_881:
	s_sleep 1
	global_load_dword v18, v17, s[10:11] sc1
	s_waitcnt vmcnt(0)
	v_cmp_ge_u32_e32 vcc, v18, v20
	s_or_b64 s[20:21], vcc, s[20:21]
	s_andn2_b64 exec, exec, s[20:21]
	s_cbranch_execnz .LBB0_881

.LBB0_886:
	s_or_b64 exec, exec, s[10:11]
	v_cmp_ne_u32_e32 vcc, 0, v15
	s_waitcnt vmcnt(0)
	v_readfirstlane_b32 s0, v17
	s_add_u32 s8, s70, 0x3500
	v_cndmask_b32_e64 v15, 0, 1, vcc
	v_cmp_ne_u32_e32 vcc, 0, v0
	s_addc_u32 s9, s71, 0
	s_nop 0
	v_addc_co_u32_e32 v0, vcc, 0, v15, vcc
	v_cmp_ne_u32_e32 vcc, 0, v1
	s_nop 1
	v_cndmask_b32_e64 v1, 0, 1, vcc
	v_cmp_ne_u32_e32 vcc, 0, v2
	v_add_u32_e32 v2, s0, v16
	s_nop 0
	v_addc_co_u32_e32 v0, vcc, v0, v1, vcc
	v_cmp_ne_u32_e32 vcc, 0, v3
	s_nop 1
	v_cndmask_b32_e64 v1, 0, 1, vcc
	v_cmp_ne_u32_e32 vcc, 0, v4
	s_nop 1
	v_addc_co_u32_e32 v0, vcc, v0, v1, vcc
	v_cmp_ne_u32_e32 vcc, 0, v5
	s_nop 1
	v_cndmask_b32_e64 v1, 0, 1, vcc
	v_cmp_ne_u32_e32 vcc, 0, v6
	s_nop 1
	v_addc_co_u32_e32 v0, vcc, v0, v1, vcc
	v_cmp_ne_u32_e32 vcc, 0, v7
	s_nop 1
	v_cndmask_b32_e64 v1, 0, 1, vcc
	v_cmp_ne_u32_e32 vcc, 0, v8
	s_nop 1
	v_addc_co_u32_e32 v0, vcc, v0, v1, vcc
	v_cmp_ne_u32_e32 vcc, 0, v9
	s_nop 1
	v_cndmask_b32_e64 v1, 0, 1, vcc
	v_cmp_ne_u32_e32 vcc, 0, v10
	s_nop 1
	v_addc_co_u32_e32 v0, vcc, v0, v1, vcc
	v_cmp_ne_u32_e32 vcc, 0, v11
	s_nop 1
	v_cndmask_b32_e64 v1, 0, 1, vcc
	v_cmp_ne_u32_e32 vcc, 0, v12
	s_nop 1
	v_addc_co_u32_e32 v0, vcc, v0, v1, vcc
	v_cmp_ne_u32_e32 vcc, 0, v13
	s_nop 1
	v_cndmask_b32_e64 v1, 0, 1, vcc
	v_cmp_ne_u32_e32 vcc, 0, v14
	s_nop 1
	v_addc_co_u32_e32 v1, vcc, v0, v1, vcc
	v_cvt_f32_u32_e32 v0, v1
	v_sub_u32_e32 v3, 0, v1
	v_rcp_iflag_f32_e32 v0, v0
	s_nop 0
	v_mul_f32_e32 v0, 0x4f7ffffe, v0
	v_cvt_u32_f32_e32 v0, v0
	v_mul_lo_u32 v3, v3, v0
	v_mul_hi_u32 v3, v0, v3
	v_add_u32_e32 v0, v0, v3
	v_mul_hi_u32 v0, v2, v0
	v_mul_lo_u32 v3, v0, v1
	v_sub_u32_e32 v3, v2, v3
	v_add_u32_e32 v4, 1, v0
	v_cmp_ge_u32_e32 vcc, v3, v1
	v_add_u32_e32 v2, 1, v2
	s_nop 0
	v_cndmask_b32_e32 v0, v0, v4, vcc
	v_sub_u32_e32 v4, v3, v1
	v_cndmask_b32_e32 v3, v3, v4, vcc
	v_add_u32_e32 v4, 1, v0
	v_cmp_ge_u32_e32 vcc, v3, v1
	s_nop 1
	v_cndmask_b32_e32 v0, v0, v4, vcc
	v_mul_lo_u32 v3, v1, v0
	v_add_u32_e32 v1, v3, v1
	v_cmp_ne_u32_e32 vcc, v2, v1
	s_and_saveexec_b64 s[0:1], vcc
	s_xor_b64 s[10:11], exec, s[0:1]
	s_cbranch_execz .LBB0_891
	v_mov_b32_e32 v4, v1
	v_mov_b32_e32 v1, 0
	global_load_dword v2, v1, s[8:9] offset:-256 sc1
	s_waitcnt vmcnt(0)
	v_cmp_lt_u32_e32 vcc, v2, v4
	s_and_saveexec_b64 s[14:15], vcc
	s_cbranch_execz .LBB0_890
	s_mov_b64 s[20:21], 0
.LBB0_889:
	s_sleep 1
	global_load_dword v2, v1, s[8:9] offset:-256 sc1
	s_waitcnt vmcnt(0)
	v_cmp_ge_u32_e32 vcc, v2, v4
	s_or_b64 s[20:21], vcc, s[20:21]
	s_andn2_b64 exec, exec, s[20:21]
	s_cbranch_execnz .LBB0_889

.LBB0_1403:
	s_or_b64 exec, exec, s[12:13]
	s_waitcnt vmcnt(0)
	s_cmp_eq_u32 s0, 0
	s_cselect_b64 vcc, -1, 0
	s_cmp_eq_u32 s0, 1
	v_cndmask_b32_e32 v18, 1, v15, vcc
	s_cselect_b64 vcc, -1, 0
	s_cmp_eq_u32 s0, 2
	v_cndmask_b32_e32 v18, v18, v0, vcc
	s_cselect_b64 vcc, -1, 0
	s_cmp_eq_u32 s0, 3
	v_cndmask_b32_e32 v18, v18, v1, vcc
	s_cselect_b64 vcc, -1, 0
	s_cmp_eq_u32 s0, 4
	v_cndmask_b32_e32 v18, v18, v2, vcc
	s_cselect_b64 vcc, -1, 0
	s_cmp_eq_u32 s0, 5
	v_cndmask_b32_e32 v18, v18, v3, vcc
	s_cselect_b64 vcc, -1, 0
	s_cmp_eq_u32 s0, 6
	v_cndmask_b32_e32 v18, v18, v4, vcc
	s_cselect_b64 vcc, -1, 0
	s_cmp_eq_u32 s0, 7
	v_cndmask_b32_e32 v18, v18, v5, vcc
	s_cselect_b64 vcc, -1, 0
	s_cmp_eq_u32 s0, 8
	v_cndmask_b32_e32 v18, v18, v6, vcc
	s_cselect_b64 vcc, -1, 0
	s_cmp_eq_u32 s0, 9
	v_cndmask_b32_e32 v18, v18, v7, vcc
	s_cselect_b64 vcc, -1, 0
	s_cmp_eq_u32 s0, 10
	v_cndmask_b32_e32 v18, v18, v8, vcc
	s_cselect_b64 vcc, -1, 0
	s_cmp_eq_u32 s0, 11
	v_cndmask_b32_e32 v18, v18, v9, vcc
	s_cselect_b64 vcc, -1, 0
	s_cmp_eq_u32 s0, 12
	v_cndmask_b32_e32 v18, v18, v10, vcc
	s_cselect_b64 vcc, -1, 0
	s_cmp_eq_u32 s0, 13
	v_cndmask_b32_e32 v18, v18, v11, vcc
	s_cselect_b64 vcc, -1, 0
	s_cmp_eq_u32 s0, 14
	v_cndmask_b32_e32 v18, v18, v12, vcc
	s_cselect_b64 vcc, -1, 0
	s_cmp_eq_u32 s0, 15
	v_cndmask_b32_e32 v18, v18, v13, vcc
	s_cselect_b64 vcc, -1, 0
	v_cndmask_b32_e32 v18, v18, v14, vcc
	v_cvt_f32_u32_e32 v19, v18
	s_waitcnt vmcnt(0)
	v_readfirstlane_b32 s0, v17
	v_rcp_iflag_f32_e32 v19, v19
	s_nop 0
	v_add_u32_e32 v17, s0, v16
	v_sub_u32_e32 v16, 0, v18
	v_mul_f32_e32 v19, 0x4f7ffffe, v19
	v_cvt_u32_f32_e32 v19, v19
	v_mul_lo_u32 v16, v16, v19
	v_mul_hi_u32 v16, v19, v16
	v_add_u32_e32 v16, v19, v16
	v_mul_hi_u32 v16, v17, v16
	v_mul_lo_u32 v19, v16, v18
	v_sub_u32_e32 v19, v17, v19
	v_add_u32_e32 v20, 1, v16
	v_cmp_ge_u32_e32 vcc, v19, v18
	v_add_u32_e32 v17, 1, v17
	s_nop 0
	v_cndmask_b32_e32 v16, v16, v20, vcc
	v_sub_u32_e32 v20, v19, v18
	v_cndmask_b32_e32 v19, v19, v20, vcc
	v_add_u32_e32 v20, 1, v16
	v_cmp_ge_u32_e32 vcc, v19, v18
	s_nop 1
	v_cndmask_b32_e32 v16, v16, v20, vcc
	v_mul_lo_u32 v19, v18, v16
	v_add_u32_e32 v18, v19, v18
	v_cmp_ne_u32_e32 vcc, v17, v18
	s_and_saveexec_b64 s[0:1], vcc
	s_xor_b64 s[10:11], exec, s[0:1]
	s_cbranch_execz .LBB0_1408
	v_cmp_ne_u32_e32 vcc, 0, v15
	s_nop 1
	v_cndmask_b32_e64 v19, 0, 1, vcc
	v_cmp_ne_u32_e32 vcc, 0, v0
	s_nop 1
	v_addc_co_u32_e32 v19, vcc, 0, v19, vcc
	v_cmp_ne_u32_e32 vcc, 0, v1
	s_nop 1
	v_addc_co_u32_e32 v19, vcc, 0, v19, vcc
	v_cmp_ne_u32_e32 vcc, 0, v2
	s_nop 1
	v_addc_co_u32_e32 v19, vcc, 0, v19, vcc
	v_cmp_ne_u32_e32 vcc, 0, v3
	s_nop 1
	v_addc_co_u32_e32 v19, vcc, 0, v19, vcc
	v_cmp_ne_u32_e32 vcc, 0, v4
	s_nop 1
	v_addc_co_u32_e32 v19, vcc, 0, v19, vcc
	v_cmp_ne_u32_e32 vcc, 0, v5
	s_nop 1
	v_addc_co_u32_e32 v19, vcc, 0, v19, vcc
	v_cmp_ne_u32_e32 vcc, 0, v6
	s_nop 1
	v_addc_co_u32_e32 v19, vcc, 0, v19, vcc
	v_cmp_ne_u32_e32 vcc, 0, v7
	s_nop 1
	v_addc_co_u32_e32 v19, vcc, 0, v19, vcc
	v_cmp_ne_u32_e32 vcc, 0, v8
	s_nop 1
	v_addc_co_u32_e32 v19, vcc, 0, v19, vcc
	v_cmp_ne_u32_e32 vcc, 0, v9
	s_nop 1
	v_addc_co_u32_e32 v19, vcc, 0, v19, vcc
	v_cmp_ne_u32_e32 vcc, 0, v10
	s_nop 1
	v_addc_co_u32_e32 v19, vcc, 0, v19, vcc
	v_cmp_ne_u32_e32 vcc, 0, v11
	s_nop 1
	v_addc_co_u32_e32 v19, vcc, 0, v19, vcc
	v_cmp_ne_u32_e32 vcc, 0, v12
	s_nop 1
	v_addc_co_u32_e32 v19, vcc, 0, v19, vcc
	v_cmp_ne_u32_e32 vcc, 0, v13
	s_nop 1
	v_addc_co_u32_e32 v19, vcc, 0, v19, vcc
	v_cmp_ne_u32_e32 vcc, 0, v14
	s_nop 1
	v_addc_co_u32_e32 v19, vcc, 0, v19, vcc
	v_add_u32_e32 v20, 1, v16
	v_mul_lo_u32 v20, v20, v19
	s_add_u32 s12, s70, 0x3400
	s_addc_u32 s13, s71, 0
	v_mov_b32_e32 v17, 0
	global_load_dword v17, v17, s[12:13] sc1
	s_waitcnt vmcnt(0)
	v_cmp_lt_u32_e32 vcc, v17, v20
	s_and_saveexec_b64 s[14:15], vcc
	s_cbranch_execz .LBB0_1407
	s_mov_b64 s[16:17], 0
	v_mov_b32_e32 v17, 0
.LBB0_1406:
	s_sleep 1
	global_load_dword v18, v17, s[12:13] sc1
	s_waitcnt vmcnt(0)
	v_cmp_ge_u32_e32 vcc, v18, v20
	s_or_b64 s[16:17], vcc, s[16:17]
	s_andn2_b64 exec, exec, s[16:17]
	s_cbranch_execnz .LBB0_1406

.LBB0_1411:
	s_or_b64 exec, exec, s[12:13]
	v_cmp_ne_u32_e32 vcc, 0, v15
	s_waitcnt vmcnt(0)
	v_readfirstlane_b32 s0, v17
	s_add_u32 s10, s70, 0x3500
	v_cndmask_b32_e64 v15, 0, 1, vcc
	v_cmp_ne_u32_e32 vcc, 0, v0
	s_addc_u32 s11, s71, 0
	s_nop 0
	v_addc_co_u32_e32 v0, vcc, 0, v15, vcc
	v_cmp_ne_u32_e32 vcc, 0, v1
	s_nop 1
	v_cndmask_b32_e64 v1, 0, 1, vcc
	v_cmp_ne_u32_e32 vcc, 0, v2
	v_add_u32_e32 v2, s0, v16
	s_nop 0
	v_addc_co_u32_e32 v0, vcc, v0, v1, vcc
	v_cmp_ne_u32_e32 vcc, 0, v3
	s_nop 1
	v_cndmask_b32_e64 v1, 0, 1, vcc
	v_cmp_ne_u32_e32 vcc, 0, v4
	s_nop 1
	v_addc_co_u32_e32 v0, vcc, v0, v1, vcc
	v_cmp_ne_u32_e32 vcc, 0, v5
	s_nop 1
	v_cndmask_b32_e64 v1, 0, 1, vcc
	v_cmp_ne_u32_e32 vcc, 0, v6
	s_nop 1
	v_addc_co_u32_e32 v0, vcc, v0, v1, vcc
	v_cmp_ne_u32_e32 vcc, 0, v7
	s_nop 1
	v_cndmask_b32_e64 v1, 0, 1, vcc
	v_cmp_ne_u32_e32 vcc, 0, v8
	s_nop 1
	v_addc_co_u32_e32 v0, vcc, v0, v1, vcc
	v_cmp_ne_u32_e32 vcc, 0, v9
	s_nop 1
	v_cndmask_b32_e64 v1, 0, 1, vcc
	v_cmp_ne_u32_e32 vcc, 0, v10
	s_nop 1
	v_addc_co_u32_e32 v0, vcc, v0, v1, vcc
	v_cmp_ne_u32_e32 vcc, 0, v11
	s_nop 1
	v_cndmask_b32_e64 v1, 0, 1, vcc
	v_cmp_ne_u32_e32 vcc, 0, v12
	s_nop 1
	v_addc_co_u32_e32 v0, vcc, v0, v1, vcc
	v_cmp_ne_u32_e32 vcc, 0, v13
	s_nop 1
	v_cndmask_b32_e64 v1, 0, 1, vcc
	v_cmp_ne_u32_e32 vcc, 0, v14
	s_nop 1
	v_addc_co_u32_e32 v1, vcc, v0, v1, vcc
	v_cvt_f32_u32_e32 v0, v1
	v_sub_u32_e32 v3, 0, v1
	v_rcp_iflag_f32_e32 v0, v0
	s_nop 0
	v_mul_f32_e32 v0, 0x4f7ffffe, v0
	v_cvt_u32_f32_e32 v0, v0
	v_mul_lo_u32 v3, v3, v0
	v_mul_hi_u32 v3, v0, v3
	v_add_u32_e32 v0, v0, v3
	v_mul_hi_u32 v0, v2, v0
	v_mul_lo_u32 v3, v0, v1
	v_sub_u32_e32 v3, v2, v3
	v_add_u32_e32 v4, 1, v0
	v_cmp_ge_u32_e32 vcc, v3, v1
	v_add_u32_e32 v2, 1, v2
	s_nop 0
	v_cndmask_b32_e32 v0, v0, v4, vcc
	v_sub_u32_e32 v4, v3, v1
	v_cndmask_b32_e32 v3, v3, v4, vcc
	v_add_u32_e32 v4, 1, v0
	v_cmp_ge_u32_e32 vcc, v3, v1
	s_nop 1
	v_cndmask_b32_e32 v0, v0, v4, vcc
	v_mul_lo_u32 v3, v1, v0
	v_add_u32_e32 v1, v3, v1
	v_cmp_ne_u32_e32 vcc, v2, v1
	s_and_saveexec_b64 s[0:1], vcc
	s_xor_b64 s[12:13], exec, s[0:1]
	s_cbranch_execz .LBB0_1416
	v_mov_b32_e32 v4, v1
	v_mov_b32_e32 v1, 0
	global_load_dword v2, v1, s[10:11] offset:-256 sc1
	s_waitcnt vmcnt(0)
	v_cmp_lt_u32_e32 vcc, v2, v4
	s_and_saveexec_b64 s[14:15], vcc
	s_cbranch_execz .LBB0_1415
	s_mov_b64 s[16:17], 0
.LBB0_1414:
	s_sleep 1
	global_load_dword v2, v1, s[10:11] offset:-256 sc1
	s_waitcnt vmcnt(0)
	v_cmp_ge_u32_e32 vcc, v2, v4
	s_or_b64 s[16:17], vcc, s[16:17]
	s_andn2_b64 exec, exec, s[16:17]
	s_cbranch_execnz .LBB0_1414

.LBB0_1463:
	s_or_b64 exec, exec, s[8:9]
	s_waitcnt vmcnt(0)
	s_cmp_eq_u32 s5, 0
	s_cselect_b64 vcc, -1, 0
	s_cmp_eq_u32 s5, 1
	v_cndmask_b32_e32 v18, 1, v15, vcc
	s_cselect_b64 vcc, -1, 0
	s_cmp_eq_u32 s5, 2
	v_cndmask_b32_e32 v18, v18, v0, vcc
	s_cselect_b64 vcc, -1, 0
	s_cmp_eq_u32 s5, 3
	v_cndmask_b32_e32 v18, v18, v1, vcc
	s_cselect_b64 vcc, -1, 0
	s_cmp_eq_u32 s5, 4
	v_cndmask_b32_e32 v18, v18, v2, vcc
	s_cselect_b64 vcc, -1, 0
	s_cmp_eq_u32 s5, 5
	v_cndmask_b32_e32 v18, v18, v3, vcc
	s_cselect_b64 vcc, -1, 0
	s_cmp_eq_u32 s5, 6
	v_cndmask_b32_e32 v18, v18, v4, vcc
	s_cselect_b64 vcc, -1, 0
	s_cmp_eq_u32 s5, 7
	v_cndmask_b32_e32 v18, v18, v5, vcc
	s_cselect_b64 vcc, -1, 0
	s_cmp_eq_u32 s5, 8
	v_cndmask_b32_e32 v18, v18, v6, vcc
	s_cselect_b64 vcc, -1, 0
	s_cmp_eq_u32 s5, 9
	v_cndmask_b32_e32 v18, v18, v7, vcc
	s_cselect_b64 vcc, -1, 0
	s_cmp_eq_u32 s5, 10
	v_cndmask_b32_e32 v18, v18, v8, vcc
	s_cselect_b64 vcc, -1, 0
	s_cmp_eq_u32 s5, 11
	v_cndmask_b32_e32 v18, v18, v9, vcc
	s_cselect_b64 vcc, -1, 0
	s_cmp_eq_u32 s5, 12
	v_cndmask_b32_e32 v18, v18, v10, vcc
	s_cselect_b64 vcc, -1, 0
	s_cmp_eq_u32 s5, 13
	v_cndmask_b32_e32 v18, v18, v11, vcc
	s_cselect_b64 vcc, -1, 0
	s_cmp_eq_u32 s5, 14
	v_cndmask_b32_e32 v18, v18, v12, vcc
	s_cselect_b64 vcc, -1, 0
	s_cmp_eq_u32 s5, 15
	v_cndmask_b32_e32 v18, v18, v13, vcc
	s_cselect_b64 vcc, -1, 0
	v_cndmask_b32_e32 v18, v18, v14, vcc
	v_cvt_f32_u32_e32 v19, v18
	s_waitcnt vmcnt(0)
	v_readfirstlane_b32 s5, v17
	v_rcp_iflag_f32_e32 v19, v19
	s_nop 0
	v_add_u32_e32 v17, s5, v16
	v_sub_u32_e32 v16, 0, v18
	v_mul_f32_e32 v19, 0x4f7ffffe, v19
	v_cvt_u32_f32_e32 v19, v19
	v_mul_lo_u32 v16, v16, v19
	v_mul_hi_u32 v16, v19, v16
	v_add_u32_e32 v16, v19, v16
	v_mul_hi_u32 v16, v17, v16
	v_mul_lo_u32 v19, v16, v18
	v_sub_u32_e32 v19, v17, v19
	v_add_u32_e32 v20, 1, v16
	v_cmp_ge_u32_e32 vcc, v19, v18
	v_add_u32_e32 v17, 1, v17
	s_nop 0
	v_cndmask_b32_e32 v16, v16, v20, vcc
	v_sub_u32_e32 v20, v19, v18
	v_cndmask_b32_e32 v19, v19, v20, vcc
	v_add_u32_e32 v20, 1, v16
	v_cmp_ge_u32_e32 vcc, v19, v18
	s_nop 1
	v_cndmask_b32_e32 v16, v16, v20, vcc
	v_mul_lo_u32 v19, v18, v16
	v_add_u32_e32 v18, v19, v18
	v_cmp_ne_u32_e32 vcc, v17, v18
	s_and_saveexec_b64 s[6:7], vcc
	s_xor_b64 s[6:7], exec, s[6:7]
	s_cbranch_execz .LBB0_1468
	v_cmp_ne_u32_e32 vcc, 0, v15
	s_nop 1
	v_cndmask_b32_e64 v19, 0, 1, vcc
	v_cmp_ne_u32_e32 vcc, 0, v0
	s_nop 1
	v_addc_co_u32_e32 v19, vcc, 0, v19, vcc
	v_cmp_ne_u32_e32 vcc, 0, v1
	s_nop 1
	v_addc_co_u32_e32 v19, vcc, 0, v19, vcc
	v_cmp_ne_u32_e32 vcc, 0, v2
	s_nop 1
	v_addc_co_u32_e32 v19, vcc, 0, v19, vcc
	v_cmp_ne_u32_e32 vcc, 0, v3
	s_nop 1
	v_addc_co_u32_e32 v19, vcc, 0, v19, vcc
	v_cmp_ne_u32_e32 vcc, 0, v4
	s_nop 1
	v_addc_co_u32_e32 v19, vcc, 0, v19, vcc
	v_cmp_ne_u32_e32 vcc, 0, v5
	s_nop 1
	v_addc_co_u32_e32 v19, vcc, 0, v19, vcc
	v_cmp_ne_u32_e32 vcc, 0, v6
	s_nop 1
	v_addc_co_u32_e32 v19, vcc, 0, v19, vcc
	v_cmp_ne_u32_e32 vcc, 0, v7
	s_nop 1
	v_addc_co_u32_e32 v19, vcc, 0, v19, vcc
	v_cmp_ne_u32_e32 vcc, 0, v8
	s_nop 1
	v_addc_co_u32_e32 v19, vcc, 0, v19, vcc
	v_cmp_ne_u32_e32 vcc, 0, v9
	s_nop 1
	v_addc_co_u32_e32 v19, vcc, 0, v19, vcc
	v_cmp_ne_u32_e32 vcc, 0, v10
	s_nop 1
	v_addc_co_u32_e32 v19, vcc, 0, v19, vcc
	v_cmp_ne_u32_e32 vcc, 0, v11
	s_nop 1
	v_addc_co_u32_e32 v19, vcc, 0, v19, vcc
	v_cmp_ne_u32_e32 vcc, 0, v12
	s_nop 1
	v_addc_co_u32_e32 v19, vcc, 0, v19, vcc
	v_cmp_ne_u32_e32 vcc, 0, v13
	s_nop 1
	v_addc_co_u32_e32 v19, vcc, 0, v19, vcc
	v_cmp_ne_u32_e32 vcc, 0, v14
	s_nop 1
	v_addc_co_u32_e32 v19, vcc, 0, v19, vcc
	v_add_u32_e32 v20, 1, v16
	v_mul_lo_u32 v20, v20, v19
	s_add_u32 s8, s70, 0x3400
	s_addc_u32 s9, s71, 0
	v_mov_b32_e32 v17, 0
	global_load_dword v17, v17, s[8:9] sc1
	s_waitcnt vmcnt(0)
	v_cmp_lt_u32_e32 vcc, v17, v20
	s_and_saveexec_b64 s[10:11], vcc
	s_cbranch_execz .LBB0_1467
	s_mov_b64 s[12:13], 0
	v_mov_b32_e32 v17, 0
.LBB0_1466:
	s_sleep 1
	global_load_dword v18, v17, s[8:9] sc1
	s_waitcnt vmcnt(0)
	v_cmp_ge_u32_e32 vcc, v18, v20
	s_or_b64 s[12:13], vcc, s[12:13]
	s_andn2_b64 exec, exec, s[12:13]
	s_cbranch_execnz .LBB0_1466

.LBB0_1471:
	s_or_b64 exec, exec, s[8:9]
	v_cmp_ne_u32_e32 vcc, 0, v15
	s_waitcnt vmcnt(0)
	v_readfirstlane_b32 s5, v17
	s_add_u32 s6, s70, 0x3500
	v_cndmask_b32_e64 v15, 0, 1, vcc
	v_cmp_ne_u32_e32 vcc, 0, v0
	s_addc_u32 s7, s71, 0
	s_nop 0
	v_addc_co_u32_e32 v0, vcc, 0, v15, vcc
	v_cmp_ne_u32_e32 vcc, 0, v1
	s_nop 1
	v_cndmask_b32_e64 v1, 0, 1, vcc
	v_cmp_ne_u32_e32 vcc, 0, v2
	v_add_u32_e32 v2, s5, v16
	s_nop 0
	v_addc_co_u32_e32 v0, vcc, v0, v1, vcc
	v_cmp_ne_u32_e32 vcc, 0, v3
	s_nop 1
	v_cndmask_b32_e64 v1, 0, 1, vcc
	v_cmp_ne_u32_e32 vcc, 0, v4
	s_nop 1
	v_addc_co_u32_e32 v0, vcc, v0, v1, vcc
	v_cmp_ne_u32_e32 vcc, 0, v5
	s_nop 1
	v_cndmask_b32_e64 v1, 0, 1, vcc
	v_cmp_ne_u32_e32 vcc, 0, v6
	s_nop 1
	v_addc_co_u32_e32 v0, vcc, v0, v1, vcc
	v_cmp_ne_u32_e32 vcc, 0, v7
	s_nop 1
	v_cndmask_b32_e64 v1, 0, 1, vcc
	v_cmp_ne_u32_e32 vcc, 0, v8
	s_nop 1
	v_addc_co_u32_e32 v0, vcc, v0, v1, vcc
	v_cmp_ne_u32_e32 vcc, 0, v9
	s_nop 1
	v_cndmask_b32_e64 v1, 0, 1, vcc
	v_cmp_ne_u32_e32 vcc, 0, v10
	s_nop 1
	v_addc_co_u32_e32 v0, vcc, v0, v1, vcc
	v_cmp_ne_u32_e32 vcc, 0, v11
	s_nop 1
	v_cndmask_b32_e64 v1, 0, 1, vcc
	v_cmp_ne_u32_e32 vcc, 0, v12
	s_nop 1
	v_addc_co_u32_e32 v0, vcc, v0, v1, vcc
	v_cmp_ne_u32_e32 vcc, 0, v13
	s_nop 1
	v_cndmask_b32_e64 v1, 0, 1, vcc
	v_cmp_ne_u32_e32 vcc, 0, v14
	s_nop 1
	v_addc_co_u32_e32 v1, vcc, v0, v1, vcc
	v_cvt_f32_u32_e32 v0, v1
	v_sub_u32_e32 v3, 0, v1
	v_rcp_iflag_f32_e32 v0, v0
	s_nop 0
	v_mul_f32_e32 v0, 0x4f7ffffe, v0
	v_cvt_u32_f32_e32 v0, v0
	v_mul_lo_u32 v3, v3, v0
	v_mul_hi_u32 v3, v0, v3
	v_add_u32_e32 v0, v0, v3
	v_mul_hi_u32 v0, v2, v0
	v_mul_lo_u32 v3, v0, v1
	v_sub_u32_e32 v3, v2, v3
	v_add_u32_e32 v4, 1, v0
	v_cmp_ge_u32_e32 vcc, v3, v1
	v_add_u32_e32 v2, 1, v2
	s_nop 0
	v_cndmask_b32_e32 v0, v0, v4, vcc
	v_sub_u32_e32 v4, v3, v1
	v_cndmask_b32_e32 v3, v3, v4, vcc
	v_add_u32_e32 v4, 1, v0
	v_cmp_ge_u32_e32 vcc, v3, v1
	s_nop 1
	v_cndmask_b32_e32 v0, v0, v4, vcc
	v_mul_lo_u32 v3, v1, v0
	v_add_u32_e32 v1, v3, v1
	v_cmp_ne_u32_e32 vcc, v2, v1
	s_and_saveexec_b64 s[8:9], vcc
	s_xor_b64 s[8:9], exec, s[8:9]
	s_cbranch_execz .LBB0_1476
	v_mov_b32_e32 v4, v1
	v_mov_b32_e32 v1, 0
	global_load_dword v2, v1, s[6:7] offset:-256 sc1
	s_waitcnt vmcnt(0)
	v_cmp_lt_u32_e32 vcc, v2, v4
	s_and_saveexec_b64 s[10:11], vcc
	s_cbranch_execz .LBB0_1475
	s_mov_b64 s[12:13], 0
.LBB0_1474:
	s_sleep 1
	global_load_dword v2, v1, s[6:7] offset:-256 sc1
	s_waitcnt vmcnt(0)
	v_cmp_ge_u32_e32 vcc, v2, v4
	s_or_b64 s[12:13], vcc, s[12:13]
	s_andn2_b64 exec, exec, s[12:13]
	s_cbranch_execnz .LBB0_1474
